# v019 plus phase-0 tile-prep loop rewritten the same way (exact code placement preserved by padding)
# speedup vs baseline: 1.0147x; 1.0055x over previous
.Lp0_rot:
	s_cmpk_ge_u32 s13, 0xc40
	s_cbranch_scc1 .Lp0_done
	s_mov_b64 s[36:37], s[44:45]
	s_mov_b64 s[38:39], s[46:47]
	v_mov_b32_e32 v46, v51
	s_mov_b32 s14, s50
	s_add_i32 s12, s12, 1
	s_min_u32 s12, s12, 2
	s_add_i32 s13, s13, s23
	s_branch .Lp0_loop
	s_nop 0
	s_nop 0
	s_nop 0
	s_nop 0
	s_nop 0
	s_nop 0
	s_nop 0
	s_nop 0
	s_nop 0
	s_nop 0
	s_nop 0
	s_nop 0
	s_nop 0
	s_nop 0
	s_nop 0
	s_nop 0
	s_nop 0
	s_nop 0
	s_nop 0
	s_nop 0
	s_nop 0
	s_nop 0
	s_nop 0
	s_nop 0
	s_nop 0
	s_nop 0
	s_nop 0
	s_nop 0
	s_nop 0
	s_nop 0
	s_nop 0
	s_nop 0
	s_nop 0
	s_nop 0
	s_nop 0
	s_nop 0
	s_nop 0
	s_nop 0
	s_nop 0
	s_nop 0
	s_nop 0
	s_nop 0
	s_nop 0
	s_nop 0
	s_nop 0
	s_nop 0
	s_nop 0
	s_nop 0
	s_nop 0
	s_nop 0
	s_nop 0
	s_nop 0
	s_nop 0
	s_nop 0
	s_nop 0
	s_nop 0
	s_nop 0
	s_nop 0
	s_nop 0
	s_nop 0
	s_nop 0
	s_nop 0
	s_nop 0
	s_nop 0
	s_nop 0
	s_nop 0
	s_nop 0
	s_nop 0
	s_nop 0
	s_nop 0
	s_nop 0
	s_nop 0
	s_nop 0
	s_nop 0
	s_nop 0
	s_nop 0
	s_nop 0
	s_nop 0
	s_nop 0
	s_nop 0
	s_nop 0
	s_nop 0
	s_nop 0
	s_nop 0
	s_nop 0
	s_nop 0
	s_nop 0
	s_nop 0
	s_nop 0
	s_nop 0
	s_nop 0
	s_nop 0
	s_nop 0
	s_nop 0
	s_nop 0
	s_nop 0
	s_nop 0
	s_nop 0
	s_nop 0
	s_nop 0
	s_nop 0
	s_nop 0
	s_nop 0
	s_nop 0
	s_nop 0
	s_nop 0
	s_nop 0
	s_nop 0
	s_nop 0
	s_nop 0
	s_nop 0
	s_nop 0
	s_nop 0
	s_nop 0
	s_nop 0
	s_nop 0
	s_nop 0
	s_nop 0
	s_nop 0
	s_nop 0
	s_nop 0
	s_nop 0
	s_nop 0
	s_nop 0
	s_nop 0
	s_nop 0
	s_nop 0
	s_nop 0
	s_nop 0
	s_nop 0
	s_nop 0
	s_nop 0
	s_nop 0
	s_nop 0
	s_nop 0
	s_nop 0
	s_nop 0
	s_nop 0
	s_nop 0
	s_nop 0
	s_nop 0
	s_nop 0
	s_nop 0
	s_nop 0
	s_nop 0
	s_nop 0
	s_nop 0
	s_nop 0
	s_nop 0
	s_nop 0
	s_nop 0
	s_nop 0
	s_nop 0
	s_nop 0
	s_nop 0
	s_nop 0
	s_nop 0
	s_nop 0
	s_nop 0
	s_nop 0
	s_nop 0
	s_nop 0
	s_nop 0
	s_nop 0
	s_nop 0
	s_nop 0
	s_nop 0
	s_nop 0
	s_nop 0
	s_nop 0
	s_nop 0
	s_nop 0
	s_nop 0
	s_nop 0
	s_nop 0
	s_nop 0
	s_nop 0
	s_nop 0
	s_nop 0
	s_nop 0
	s_nop 0
	s_nop 0
	s_nop 0
	s_nop 0
	s_nop 0
	s_nop 0
	s_nop 0
	s_nop 0
	s_nop 0
	s_nop 0
	s_nop 0
	s_nop 0
	s_nop 0
	s_nop 0
	s_nop 0
	s_nop 0
	s_nop 0
	s_nop 0
	s_nop 0
	s_nop 0
	s_nop 0
	s_nop 0
	s_nop 0
	s_nop 0
	s_nop 0
	s_nop 0
	s_nop 0
	s_nop 0
	s_nop 0
	s_nop 0
	s_nop 0
	s_nop 0
	s_nop 0
	s_nop 0
	s_nop 0
	s_nop 0
	s_nop 0
	s_nop 0
	s_nop 0
	s_nop 0
	s_nop 0
	s_nop 0
	s_nop 0
	s_nop 0
	s_nop 0
	s_nop 0
	s_nop 0
	s_nop 0
	s_nop 0
	s_nop 0
	s_nop 0
	s_nop 0
	s_nop 0
	s_nop 0
	s_nop 0
	s_nop 0
	s_nop 0
	s_nop 0
	s_nop 0
	s_nop 0
	s_nop 0
	s_nop 0
	s_nop 0
	s_nop 0
	s_nop 0
	s_nop 0
	s_nop 0
	s_nop 0
	s_nop 0
	s_nop 0
	s_nop 0
	s_nop 0
	s_nop 0
	s_nop 0
	s_nop 0
	s_nop 0
	s_nop 0
	s_nop 0
	s_nop 0
	s_nop 0
	s_nop 0
	s_nop 0
	s_nop 0
	s_nop 0
	s_nop 0
	s_nop 0
	s_nop 0
	s_nop 0
	s_nop 0
	s_nop 0
	s_nop 0
	s_nop 0
	s_nop 0
	s_nop 0
	s_nop 0
	s_nop 0
	s_nop 0
	s_nop 0
	s_nop 0
	s_nop 0
	s_nop 0
	s_nop 0
	s_nop 0
	s_nop 0
	s_nop 0
	s_nop 0
	s_nop 0
	s_nop 0
	s_nop 0
	s_nop 0
	s_nop 0
	s_nop 0
	s_nop 0
	s_nop 0
	s_nop 0
	s_nop 0
	s_nop 0
	s_nop 0
	s_nop 0
	s_nop 0
	s_nop 0
	s_nop 0
	s_nop 0
	s_nop 0
	s_nop 0
	s_nop 0
	s_nop 0
	s_nop 0
	s_nop 0
	s_nop 0
	s_nop 0
	s_nop 0
	s_nop 0
	s_nop 0
	s_nop 0
	s_nop 0
	s_nop 0
	s_nop 0
	s_nop 0
	s_nop 0
	s_nop 0
	s_nop 0
	s_nop 0
	s_nop 0
	s_nop 0
	s_nop 0
	s_nop 0
	s_nop 0
	s_nop 0
	s_nop 0
	s_nop 0
	s_nop 0
	s_nop 0
	s_nop 0
	s_nop 0
	s_nop 0
	s_nop 0
	s_nop 0
	s_nop 0
	s_nop 0
	s_nop 0
	s_nop 0
	s_nop 0
	s_nop 0
	s_nop 0
	s_nop 0
	s_nop 0
	s_nop 0
	s_nop 0
	s_nop 0
	s_nop 0
	s_nop 0
	s_nop 0
	s_nop 0
	s_nop 0
	s_nop 0
	s_nop 0
	s_nop 0
	s_nop 0
	s_nop 0
	s_nop 0
	s_nop 0
	s_nop 0
	s_nop 0
	s_nop 0
	s_nop 0
	s_nop 0
	s_nop 0
	s_nop 0
	s_nop 0
	s_nop 0
	s_nop 0
	s_nop 0
	s_nop 0
	s_nop 0
	s_nop 0
	s_nop 0
	s_nop 0
	s_nop 0
	s_nop 0
	s_nop 0
	s_nop 0
	s_nop 0
	s_nop 0
	s_nop 0
	s_nop 0
	s_nop 0
	s_nop 0
	s_nop 0
	s_nop 0
	s_nop 0
	s_nop 0
	s_nop 0
	s_nop 0
	s_nop 0
	s_nop 0
	s_nop 0
	s_nop 0
	s_nop 0
	s_nop 0
	s_nop 0
	s_nop 0
	s_nop 0
	s_nop 0
	s_nop 0
	s_nop 0
	s_nop 0
	s_nop 0
	s_nop 0
	s_nop 0
	s_nop 0
	s_nop 0
	s_nop 0
	s_nop 0
	s_nop 0
	s_nop 0
	s_nop 0
	s_nop 0
	s_nop 0
	s_nop 0
	s_nop 0
	s_nop 0
	s_nop 0
	s_nop 0
	s_nop 0
	s_nop 0
	s_nop 0
	s_nop 0
	s_nop 0
	s_nop 0
	s_nop 0
	s_nop 0
	s_nop 0
	s_nop 0
	s_nop 0
	s_nop 0
	s_nop 0
	s_nop 0
	s_nop 0
	s_nop 0
	s_nop 0
	s_nop 0
	s_nop 0
	s_nop 0
	s_nop 0
	s_nop 0
	s_nop 0
	s_nop 0
	s_nop 0
	s_nop 0
	s_nop 0
	s_nop 0
	s_nop 0
	s_nop 0
	s_nop 0
	s_nop 0
	s_nop 0
	s_nop 0
	s_nop 0
	s_nop 0
	s_nop 0
	s_nop 0
	s_nop 0
	s_nop 0
	s_nop 0
	s_nop 0
	s_nop 0
	s_nop 0
	s_nop 0
	s_nop 0
	s_nop 0
	s_nop 0
	s_nop 0
	s_nop 0
	s_nop 0
	s_nop 0
	s_nop 0
	s_nop 0
	s_nop 0
	s_nop 0
	s_nop 0
	s_nop 0
	s_nop 0
	s_nop 0
	s_nop 0
	s_nop 0
	s_nop 0
	s_nop 0
	s_nop 0
	s_nop 0
	s_nop 0
	s_nop 0
	s_nop 0
	s_nop 0
	s_nop 0
	s_nop 0
	s_nop 0
	s_nop 0
	s_nop 0
	s_nop 0
	s_nop 0
	s_nop 0
	s_nop 0
	s_nop 0
	s_nop 0
	s_nop 0
	s_nop 0
	s_nop 0
	s_nop 0
	s_nop 0
	s_nop 0
	s_nop 0
	s_nop 0
	s_nop 0
	s_nop 0
	s_nop 0
	s_nop 0
	s_nop 0
	s_nop 0
	s_nop 0
	s_nop 0
	s_nop 0
	s_nop 0
	s_nop 0
	s_nop 0
	s_nop 0
	s_nop 0
	s_nop 0
	s_nop 0
	s_nop 0
	s_nop 0
	s_nop 0
	s_nop 0
	s_nop 0
	s_nop 0
	s_nop 0
	s_nop 0
	s_nop 0
	s_nop 0
	s_nop 0
	s_nop 0
	s_nop 0
	s_nop 0
	s_nop 0
	s_nop 0
	s_nop 0
	s_nop 0
	s_nop 0
	s_nop 0
	s_nop 0
	s_nop 0
	s_nop 0
	s_nop 0
	s_nop 0
	s_nop 0
	s_nop 0
	s_nop 0
	s_nop 0
	s_nop 0
	s_nop 0
	s_nop 0
	s_nop 0
	s_nop 0
	s_nop 0
	s_nop 0
	s_nop 0
	s_nop 0
	s_nop 0
	s_nop 0
	s_nop 0
	s_nop 0
	s_nop 0
	s_nop 0
	s_nop 0
	s_nop 0
	s_nop 0
	s_nop 0
	s_nop 0
	s_nop 0
	s_nop 0
	s_nop 0
	s_nop 0
	s_nop 0
	s_nop 0
	s_nop 0
	s_nop 0
	s_nop 0
	s_nop 0
	s_nop 0
	s_nop 0
	s_nop 0
	s_nop 0
	s_nop 0
	s_nop 0
	s_nop 0
	s_nop 0
	s_nop 0
	s_nop 0
	s_nop 0
	s_nop 0
	s_nop 0
	s_nop 0
	s_nop 0
	s_nop 0
	s_nop 0
	s_nop 0
	s_nop 0
	s_nop 0
	s_nop 0
	s_nop 0
	s_nop 0
	s_nop 0
	s_nop 0
	s_nop 0
	s_nop 0
	s_nop 0
	s_nop 0
	s_nop 0
	s_nop 0
	s_nop 0
	s_nop 0
	s_nop 0
	s_nop 0
	s_nop 0
	s_nop 0
	s_nop 0
	s_nop 0
	s_nop 0
	s_nop 0
	s_nop 0
	s_nop 0
	s_nop 0
	s_nop 0
	s_nop 0
	s_nop 0
	s_nop 0
	s_nop 0
	s_nop 0
	s_nop 0
	s_nop 0
	s_nop 0
	s_nop 0
	s_nop 0
	s_nop 0
	s_nop 0
	s_nop 0
	s_nop 0
	s_nop 0
	s_nop 0
	s_nop 0
	s_nop 0
	s_nop 0
	s_nop 0
	s_nop 0
	s_nop 0
	s_nop 0
	s_nop 0
	s_nop 0
	s_nop 0
	s_nop 0
	s_nop 0
	s_nop 0
	s_nop 0
	s_nop 0
	s_nop 0
	s_nop 0
	s_nop 0
	s_nop 0
	s_nop 0
	s_nop 0
	s_nop 0
	s_nop 0
	s_nop 0
	s_nop 0
	s_nop 0
	s_nop 0
	s_nop 0
	s_nop 0
